# sweep 2 far tiles: QK(keys 32-63) MFMAs interleaved into softmax VALU of keys 0-31, PV(keys 0-31) MFMAs into softmax VALU of keys 32-63
# speedup vs baseline: 1.0079x; 1.0079x over previous
; #define KLOAD(t) do { const bf16* kp_ = Kb + (size_t)((t) * 64 + sr) * 1024 + sc; ks0 = *reinterpret_cast<const bf16x8*>(kp_); ks1 = *reinterpret_cast<const bf16x8*>(kp_ + 32 * 1024); } while (0)
; #define VLOAD(t) do { const bf16* vp_ = Vb + (size_t)((t) * 64 + sr) * 1024 + sc; vs0 = *reinterpret_cast<const bf16x8*>(vp_); vs1 = *reinterpret_cast<const bf16x8*>(vp_ + 32 * 1024); } while (0)
; #define KWRITE() do { *reinterpret_cast<bf16x8*>(K_lds + kst0) = ks0; *reinterpret_cast<bf16x8*>(K_lds + kst1) = ks1; } while (0)
; #define VWRITE() do { *reinterpret_cast<bf16x8*>(V_lds + vst0) = vs0; *reinterpret_cast<bf16x8*>(V_lds + vst1) = vs1; } while (0)
; template <bool DIFF> ...
;     ...
;   for (int t = t_lo; t < t_hi; ++t) {
;     __syncthreads();
;     KWRITE(); VWRITE();
;     __syncthreads();
;     if (t + 1 < t_hi) { KLOAD(t + 1); VLOAD(t + 1); }
;     const bool active = DIFF || (t >= rstart && t < rstart + 8);
;     if (active) {
;       bf16x8 pa0, pa1, pa2, pa3;
;     ...
;       f32x16 a0, b0, a1, b1;
;       qkt<DIFF>(a0, b0, K_lds, Q_lds, r32, r32, hi);
;       qkt<DIFF>(a1, b1, K_lds, Q_lds, r32 + 32, r32, hi);
.LBB0_310:
	s_barrier
	s_waitcnt vmcnt(3)
	ds_write_b128 v174, v[128:131]
	s_waitcnt vmcnt(2)
	ds_write_b128 v175, v[132:135]
	s_waitcnt vmcnt(1)
	ds_write_b128 v189, v[136:139] offset:16384
	s_waitcnt vmcnt(0)
	ds_write_b128 v190, v[140:143] offset:16384
	s_waitcnt lgkmcnt(0)
	s_barrier
	s_cmpk_ge_i32 s93, 0x9f
	s_cbranch_scc1 .Lsw2f_hi
	s_cmpk_le_i32 s93, 0xff41
	s_cbranch_scc1 .Lsw2f_lo
	ds_read_b128 v[64:67], v176
	ds_read_b128 v[68:71], v172 offset:36864
	ds_read_b128 v[72:75], v177
	ds_read_b128 v[76:79], v176 offset:8192
	s_waitcnt lgkmcnt(2)
	v_mfma_f32_32x32x16_bf16 v[112:127], v[64:67], v[68:71], 0
	ds_read_b128 v[64:67], v171 offset:36864
	ds_read_b128 v[128:131], v177 offset:8192
	s_waitcnt lgkmcnt(1)
	v_mfma_f32_32x32x16_bf16 v[96:111], v[72:75], v[64:67], 0
	ds_read_b128 v[72:75], v178
	ds_read_b128 v[132:135], v170 offset:36864
	ds_read_b128 v[80:83], v179
	ds_read_b128 v[136:139], v178 offset:8192
	ds_read_b128 v[140:143], v169 offset:36864
	ds_read_b128 v[192:195], v179 offset:8192
	s_waitcnt lgkmcnt(1)
	v_mfma_f32_32x32x16_bf16 v[96:111], v[80:83], v[140:143], v[96:111]
	v_mfma_f32_32x32x16_bf16 v[112:127], v[72:75], v[132:135], v[112:127]
	ds_read_b128 v[72:75], v180
	ds_read_b128 v[196:199], v168 offset:36864
	ds_read_b128 v[80:83], v181
	ds_read_b128 v[200:203], v180 offset:8192
	ds_read_b128 v[204:207], v167 offset:36864
	ds_read_b128 v[210:213], v181 offset:8192
	s_waitcnt lgkmcnt(1)
	v_mfma_f32_32x32x16_bf16 v[96:111], v[80:83], v[204:207], v[96:111]
	v_mfma_f32_32x32x16_bf16 v[112:127], v[72:75], v[196:199], v[112:127]
	ds_read_b128 v[72:75], v182
	ds_read_b128 v[214:217], v166 offset:36864
	ds_read_b128 v[80:83], v183
	ds_read_b128 v[218:221], v182 offset:8192
	ds_read_b128 v[222:225], v149 offset:36864
	ds_read_b128 v[226:229], v183 offset:8192
	s_waitcnt lgkmcnt(1)
	v_mfma_f32_32x32x16_bf16 v[96:111], v[80:83], v[222:225], v[96:111]
	v_mfma_f32_32x32x16_bf16 v[80:95], v[76:79], v[68:71], 0
	v_mfma_f32_32x32x16_bf16 v[112:127], v[72:75], v[214:217], v[112:127]
	v_mfma_f32_32x32x16_bf16 v[64:79], v[128:131], v[64:67], 0
	v_lshl_add_u64 v[128:129], v[150:151], 0, s[34:35]
	v_add_co_u32_e32 v130, vcc, s70, v128
	s_nop 1
	v_addc_co_u32_e32 v131, vcc, 0, v129, vcc
	v_mfma_f32_32x32x16_bf16 v[80:95], v[136:139], v[132:135], v[80:95]
	v_add_co_u32_e32 v132, vcc, s71, v128
	v_lshl_add_u64 v[136:137], v[152:153], 0, s[34:35]
	s_nop 0
	v_addc_co_u32_e32 v133, vcc, 0, v129, vcc
	v_add_co_u32_e32 v138, vcc, s72, v136
	v_mfma_f32_32x32x16_bf16 v[64:79], v[192:195], v[140:143], v[64:79]
	s_nop 0
	v_addc_co_u32_e32 v139, vcc, 0, v137, vcc
	v_add_co_u32_e32 v140, vcc, s73, v136
	global_load_dwordx4 v[128:131], v[130:131], off
	s_nop 0
	global_load_dwordx4 v[132:135], v[132:133], off
	v_addc_co_u32_e32 v141, vcc, 0, v137, vcc
	global_load_dwordx4 v[136:139], v[138:139], off
	s_nop 0
	global_load_dwordx4 v[140:143], v[140:141], off
	v_mfma_f32_32x32x16_bf16 v[80:95], v[200:203], v[196:199], v[80:95]
	v_mfma_f32_32x32x16_bf16 v[64:79], v[210:213], v[204:207], v[64:79]
	v_mfma_f32_32x32x16_bf16 v[80:95], v[218:221], v[214:217], v[80:95]
	s_waitcnt lgkmcnt(0)
	v_mfma_f32_32x32x16_bf16 v[64:79], v[226:229], v[222:225], v[64:79]
	s_cmpk_ge_i32 s93, 0x9f
	s_cbranch_scc1 .Lb2a_hi
	s_cmpk_le_i32 s93, 0xff41
	s_cbranch_scc1 .Lb2a_lo
	v_add3_u32 v192, v191, v173, s55
	v_med3_i32 v193, v192, 0, v163
	v_lshl_add_u32 v200, v193, 2, 0
	v_max_i32_e32 v193, -1, v192
	v_add_u32_e32 v193, 1, v193
	v_min_u32_e32 v193, 0x100, v193
	v_lshl_add_u32 v201, v193, 2, 0
	v_max_i32_e32 v193, -2, v192
	v_add_u32_e32 v193, 2, v193
	v_min_u32_e32 v193, 0x100, v193
	v_lshl_add_u32 v202, v193, 2, 0
	v_max_i32_e32 v193, -3, v192
	v_add_u32_e32 v193, 3, v193
	v_min_u32_e32 v193, 0x100, v193
	v_lshl_add_u32 v203, v193, 2, 0
	v_max_i32_e32 v193, -8, v192
	v_add_u32_e32 v193, 8, v193
	v_min_u32_e32 v193, 0x100, v193
	v_lshl_add_u32 v204, v193, 2, 0
	v_max_i32_e32 v193, -9, v192
	v_add_u32_e32 v193, 9, v193
	v_min_u32_e32 v193, 0x100, v193
	v_lshl_add_u32 v205, v193, 2, 0
	v_max_i32_e32 v193, -10, v192
	v_add_u32_e32 v193, 10, v193
	v_min_u32_e32 v193, 0x100, v193
	v_lshl_add_u32 v206, v193, 2, 0
	v_max_i32_e32 v193, -11, v192
	v_add_u32_e32 v193, 11, v193
	v_min_u32_e32 v193, 0x100, v193
	v_lshl_add_u32 v207, v193, 2, 0
	v_max_i32_e32 v193, -16, v192
	v_max_i32_e32 v194, 0xffffffef, v192
	v_max_i32_e32 v195, 0xffffffee, v192
	v_max_i32_e32 v196, 0xffffffed, v192
	v_max_i32_e32 v197, 0xffffffe8, v192
	v_max_i32_e32 v198, 0xffffffe7, v192
	v_max_i32_e32 v199, 0xffffffe6, v192
	v_add_u32_e32 v193, 16, v193
	v_add_u32_e32 v194, 17, v194
	v_add_u32_e32 v195, 18, v195
	v_add_u32_e32 v196, 19, v196
	v_add_u32_e32 v197, 24, v197
	v_add_u32_e32 v198, 25, v198
	v_add_u32_e32 v199, 26, v199
	v_max_i32_e32 v192, 0xffffffe5, v192
	v_min_u32_e32 v193, 0x100, v193
	v_min_u32_e32 v194, 0x100, v194
	v_min_u32_e32 v195, 0x100, v195
	v_min_u32_e32 v196, 0x100, v196
	v_min_u32_e32 v197, 0x100, v197
	v_min_u32_e32 v198, 0x100, v198
	v_min_u32_e32 v199, 0x100, v199
	v_add_u32_e32 v192, 27, v192
	v_lshl_add_u32 v193, v193, 2, 0
	v_lshl_add_u32 v194, v194, 2, 0
	v_lshl_add_u32 v195, v195, 2, 0
	v_lshl_add_u32 v196, v196, 2, 0
	v_lshl_add_u32 v197, v197, 2, 0
	v_lshl_add_u32 v198, v198, 2, 0
	v_lshl_add_u32 v199, v199, 2, 0
	v_min_u32_e32 v192, 0x100, v192
	v_lshl_add_u32 v209, v192, 2, 0
	ds_read_b32 v192, v193 offset:32768
	ds_read_b32 v193, v194 offset:32768
	ds_read_b32 v194, v195 offset:32768
	ds_read_b32 v195, v196 offset:32768
	ds_read_b32 v196, v197 offset:32768
	ds_read_b32 v197, v198 offset:32768
	ds_read_b32 v198, v199 offset:32768
	ds_read_b32 v199, v209 offset:32768
	ds_read_b32 v200, v200 offset:32768
	ds_read_b32 v201, v201 offset:32768
	ds_read_b32 v202, v202 offset:32768
	ds_read_b32 v203, v203 offset:32768
	ds_read_b32 v204, v204 offset:32768
	ds_read_b32 v205, v205 offset:32768
	ds_read_b32 v206, v206 offset:32768
	ds_read_b32 v207, v207 offset:32768
	s_waitcnt lgkmcnt(8)
	v_pk_add_f32 v[126:127], v[126:127], v[198:199]
	v_pk_add_f32 v[124:125], v[124:125], v[196:197]
	v_pk_add_f32 v[122:123], v[122:123], v[194:195]
	v_pk_add_f32 v[120:121], v[120:121], v[192:193]
	s_waitcnt lgkmcnt(0)
	v_pk_add_f32 v[118:119], v[118:119], v[206:207]
	v_pk_add_f32 v[116:117], v[116:117], v[204:205]
	v_pk_add_f32 v[114:115], v[114:115], v[202:203]
	v_pk_add_f32 v[112:113], v[112:113], v[200:201]
	v_pk_add_f32 v[110:111], v[110:111], v[198:199]
	v_pk_add_f32 v[108:109], v[108:109], v[196:197]
	v_pk_add_f32 v[106:107], v[106:107], v[194:195]
	v_pk_add_f32 v[104:105], v[104:105], v[192:193]
	v_pk_add_f32 v[102:103], v[102:103], v[206:207]
	v_pk_add_f32 v[100:101], v[100:101], v[204:205]
	v_pk_add_f32 v[98:99], v[98:99], v[202:203]
	v_pk_add_f32 v[96:97], v[96:97], v[200:201]
	v_mov_b32_e32 v192, 0
	s_branch .LBB0_318

; #define SBAR() __builtin_amdgcn_sched_barrier(0)
; template <bool DIFF> ...
;     ...
;       qkt<DIFF>(a0, b0, K_lds, Q_lds, r32, r32, hi);
;       qkt<DIFF>(a1, b1, K_lds, Q_lds, r32 + 32, r32, hi);
;       SBAR();
;     ...
;       BIAS_APPLY(t, 0, a0, b0, cb0);
;       { const float x1 = fmaf(cb0, C, e1), x2 = fmaf(cb0, C, e2);
; #pragma unroll
;       for (int r = 0; r < 16; ++r) a0[r] = __builtin_amdgcn_exp2f(fmaf(a0[r], C, x1));
;       if (DIFF) {
; #pragma unroll
;         for (int r = 0; r < 16; ++r) a0[r] = fmaf(nsg, __builtin_amdgcn_exp2f(fmaf(b0[r], C, x2)), a0[r]);
;       } }
;       PK4(a0, 0, pa0); PK4(a0, 8, pa1);
.Lsw2f_hi:
	v_mov_b32_e32 v234, v253
	v_mov_b32_e32 v236, v253
	s_branch .Lsw2f
.Lsw2f_lo:
	v_mov_b32_e32 v234, v252
	v_mov_b32_e32 v236, v252
.Lsw2f:
	ds_read_b128 v[64:67], v176
	ds_read_b128 v[68:71], v172 offset:36864
	ds_read_b128 v[72:75], v177
	ds_read_b128 v[76:79], v176 offset:8192
	s_waitcnt lgkmcnt(2)
	v_mfma_f32_32x32x16_bf16 v[112:127], v[64:67], v[68:71], 0
	ds_read_b128 v[64:67], v171 offset:36864
	ds_read_b128 v[128:131], v177 offset:8192
	s_waitcnt lgkmcnt(1)
	v_mfma_f32_32x32x16_bf16 v[96:111], v[72:75], v[64:67], 0
	ds_read_b128 v[72:75], v178
	ds_read_b128 v[132:135], v170 offset:36864
	ds_read_b128 v[80:83], v179
	ds_read_b128 v[136:139], v178 offset:8192
	ds_read_b128 v[140:143], v169 offset:36864
	ds_read_b128 v[192:195], v179 offset:8192
	s_waitcnt lgkmcnt(1)
	v_mfma_f32_32x32x16_bf16 v[96:111], v[80:83], v[140:143], v[96:111]
	v_mfma_f32_32x32x16_bf16 v[112:127], v[72:75], v[132:135], v[112:127]
	ds_read_b128 v[72:75], v180
	ds_read_b128 v[196:199], v168 offset:36864
	ds_read_b128 v[80:83], v181
	ds_read_b128 v[200:203], v180 offset:8192
	ds_read_b128 v[204:207], v167 offset:36864
	ds_read_b128 v[210:213], v181 offset:8192
	s_waitcnt lgkmcnt(1)
	v_mfma_f32_32x32x16_bf16 v[96:111], v[80:83], v[204:207], v[96:111]
	v_mfma_f32_32x32x16_bf16 v[112:127], v[72:75], v[196:199], v[112:127]
	ds_read_b128 v[72:75], v182
	ds_read_b128 v[214:217], v166 offset:36864
	ds_read_b128 v[80:83], v183
	ds_read_b128 v[218:221], v182 offset:8192
	ds_read_b128 v[222:225], v149 offset:36864
	ds_read_b128 v[226:229], v183 offset:8192
	s_waitcnt lgkmcnt(1)
	v_mfma_f32_32x32x16_bf16 v[96:111], v[80:83], v[222:225], v[96:111]
	v_mfma_f32_32x32x16_bf16 v[112:127], v[72:75], v[214:217], v[112:127]
	s_waitcnt lgkmcnt(0)
	v_mfma_f32_32x32x16_bf16 v[80:95], v[76:79], v[68:71], 0
	v_fmamk_f32 v235, v234, 0x3e38aa3b, v188
	v_fmamk_f32 v234, v234, 0x3e38aa3b, v187
	s_nop 8
	v_fmamk_f32 v112, v112, 0x3e38aa3b, v235
	v_fmamk_f32 v113, v113, 0x3e38aa3b, v235
	v_fmamk_f32 v114, v114, 0x3e38aa3b, v235
	v_fmamk_f32 v115, v115, 0x3e38aa3b, v235
	v_fmamk_f32 v116, v116, 0x3e38aa3b, v235
	v_fmamk_f32 v117, v117, 0x3e38aa3b, v235
	v_fmamk_f32 v96, v96, 0x3e38aa3b, v234
	v_fmamk_f32 v97, v97, 0x3e38aa3b, v234
	v_fmamk_f32 v98, v98, 0x3e38aa3b, v234
	v_fmamk_f32 v99, v99, 0x3e38aa3b, v234
	v_fmamk_f32 v100, v100, 0x3e38aa3b, v234
	v_fmamk_f32 v101, v101, 0x3e38aa3b, v234
	v_exp_f32_e32 v112, v112
	v_mfma_f32_32x32x16_bf16 v[64:79], v[128:131], v[64:67], 0
	v_exp_f32_e32 v113, v113
	v_exp_f32_e32 v114, v114
	v_exp_f32_e32 v115, v115
	v_exp_f32_e32 v116, v116
	v_exp_f32_e32 v117, v117
	v_fmamk_f32 v118, v118, 0x3e38aa3b, v235
	v_fmamk_f32 v119, v119, 0x3e38aa3b, v235
	v_fmamk_f32 v120, v120, 0x3e38aa3b, v235
	v_fmamk_f32 v121, v121, 0x3e38aa3b, v235
	v_fmamk_f32 v122, v122, 0x3e38aa3b, v235
	v_mfma_f32_32x32x16_bf16 v[80:95], v[136:139], v[132:135], v[80:95]
	v_fmamk_f32 v123, v123, 0x3e38aa3b, v235
	v_fmamk_f32 v124, v124, 0x3e38aa3b, v235
	v_fmamk_f32 v125, v125, 0x3e38aa3b, v235
	v_fmamk_f32 v126, v126, 0x3e38aa3b, v235
	v_fmac_f32_e32 v235, 0x3e38aa3b, v127
	v_exp_f32_e32 v96, v96
	v_exp_f32_e32 v97, v97
	v_exp_f32_e32 v98, v98
	v_exp_f32_e32 v99, v99
	v_exp_f32_e32 v100, v100
	v_exp_f32_e32 v101, v101
	v_mfma_f32_32x32x16_bf16 v[64:79], v[192:195], v[140:143], v[64:79]
	v_lshl_add_u64 v[128:129], v[150:151], 0, s[34:35]
	v_add_co_u32_e32 v130, vcc, s70, v128
	s_nop 1
	v_addc_co_u32_e32 v131, vcc, 0, v129, vcc
	v_add_co_u32_e32 v132, vcc, s71, v128
	v_lshl_add_u64 v[136:137], v[152:153], 0, s[34:35]
	s_nop 0
	v_addc_co_u32_e32 v133, vcc, 0, v129, vcc
	v_add_co_u32_e32 v138, vcc, s72, v136
	s_nop 1
	v_addc_co_u32_e32 v139, vcc, 0, v137, vcc
	v_add_co_u32_e32 v140, vcc, s73, v136
	global_load_dwordx4 v[128:131], v[130:131], off
	s_nop 0
	global_load_dwordx4 v[132:135], v[132:133], off
	v_addc_co_u32_e32 v141, vcc, 0, v137, vcc
	global_load_dwordx4 v[136:139], v[138:139], off
	s_nop 0
	global_load_dwordx4 v[140:143], v[140:141], off
	v_fmamk_f32 v102, v102, 0x3e38aa3b, v234
	v_fmamk_f32 v103, v103, 0x3e38aa3b, v234
	v_fmamk_f32 v104, v104, 0x3e38aa3b, v234
	v_fmamk_f32 v105, v105, 0x3e38aa3b, v234
	v_fmamk_f32 v106, v106, 0x3e38aa3b, v234
	v_fmamk_f32 v107, v107, 0x3e38aa3b, v234
	v_fmamk_f32 v108, v108, 0x3e38aa3b, v234
	v_fmamk_f32 v109, v109, 0x3e38aa3b, v234
	v_fmamk_f32 v110, v110, 0x3e38aa3b, v234
	v_fmac_f32_e32 v234, 0x3e38aa3b, v111
	v_exp_f32_e32 v118, v118
	v_exp_f32_e32 v119, v119
	v_exp_f32_e32 v120, v120
	v_mfma_f32_32x32x16_bf16 v[80:95], v[200:203], v[196:199], v[80:95]
	v_exp_f32_e32 v121, v121
	v_exp_f32_e32 v122, v122
	v_exp_f32_e32 v123, v123
	v_exp_f32_e32 v124, v124
	v_exp_f32_e32 v125, v125
	v_exp_f32_e32 v126, v126
	v_exp_f32_e32 v127, v235
	v_exp_f32_e32 v102, v102
	v_mfma_f32_32x32x16_bf16 v[64:79], v[210:213], v[204:207], v[64:79]
	v_exp_f32_e32 v103, v103
	v_exp_f32_e32 v104, v104
	v_exp_f32_e32 v105, v105
	v_exp_f32_e32 v106, v106
	v_exp_f32_e32 v107, v107
	v_exp_f32_e32 v108, v108
	v_exp_f32_e32 v109, v109
	v_exp_f32_e32 v110, v110
	v_mfma_f32_32x32x16_bf16 v[80:95], v[218:221], v[214:217], v[80:95]
	v_exp_f32_e32 v111, v234
	v_pk_fma_f32 v[96:97], v[144:145], v[96:97], v[112:113]
	v_pk_fma_f32 v[98:99], v[144:145], v[98:99], v[114:115]
	v_pk_fma_f32 v[100:101], v[144:145], v[100:101], v[116:117]
	v_pk_fma_f32 v[102:103], v[144:145], v[102:103], v[118:119]
	v_pk_fma_f32 v[104:105], v[144:145], v[104:105], v[120:121]
	v_pk_fma_f32 v[106:107], v[144:145], v[106:107], v[122:123]
	v_pk_fma_f32 v[108:109], v[144:145], v[108:109], v[124:125]
	v_mfma_f32_32x32x16_bf16 v[64:79], v[226:229], v[222:225], v[64:79]
; #define SBAR() __builtin_amdgcn_sched_barrier(0)
; template <int KS> __device__ __forceinline__ void pv_step(f32x16* o, int vb, bf16x8 pa) {
;   const s16x4 l0 = tr_read<v_rd_off(0, KS, 0)>(vb), h0 = tr_read<v_rd_off(0, KS, 1)>(vb), l1 = tr_read<v_rd_off(1, KS, 0)>(vb), h1 = tr_read<v_rd_off(1, KS, 1)>(vb);
;   const s16x4 l2 = tr_read<v_rd_off(2, KS, 0)>(vb), h2 = tr_read<v_rd_off(2, KS, 1)>(vb), l3 = tr_read<v_rd_off(3, KS, 0)>(vb), h3 = tr_read<v_rd_off(3, KS, 1)>(vb);
;   asm volatile("s_waitcnt lgkmcnt(0)" ::: "memory"); SBAR();
;     ...
;   o[0] = __builtin_amdgcn_mfma_f32_32x32x16_bf16(pa, PK(l0, h0), o[0], 0, 0, 0);
;   o[1] = __builtin_amdgcn_mfma_f32_32x32x16_bf16(pa, PK(l1, h1), o[1], 0, 0, 0);
;   o[2] = __builtin_amdgcn_mfma_f32_32x32x16_bf16(pa, PK(l2, h2), o[2], 0, 0, 0);
;   o[3] = __builtin_amdgcn_mfma_f32_32x32x16_bf16(pa, PK(l3, h3), o[3], 0, 0, 0);
;     ...
; }
; template <bool DIFF> ...
;     ...
;       PK4(a0, 0, pa0); PK4(a0, 8, pa1);
;       SBAR();
;       pv_step<0>(o, vb0, pa0); pv_step<1>(o, vb0, pa1);
;       SBAR();
;       BIAS_APPLY(t, 1, a1, b1, cb1);
;       { const float x1 = fmaf(cb1, C, e1), x2 = fmaf(cb1, C, e2);
; #pragma unroll
;       for (int r = 0; r < 16; ++r) a1[r] = __builtin_amdgcn_exp2f(fmaf(a1[r], C, x1));
;       if (DIFF) {
; #pragma unroll
;         for (int r = 0; r < 16; ++r) a1[r] = fmaf(nsg, __builtin_amdgcn_exp2f(fmaf(b1[r], C, x2)), a1[r]);
;       } }
;       PK4(a1, 0, pa2); PK4(a1, 8, pa3);
;       SBAR();
;       pv_step<2>(o, vb0, pa2); pv_step<3>(o, vb0, pa3);
	v_pk_fma_f32 v[110:111], v[144:145], v[110:111], v[126:127]
	v_cvt_pk_bf16_f32 v96, v96, v97
	v_cvt_pk_bf16_f32 v97, v98, v99
	v_cvt_pk_bf16_f32 v98, v100, v101
	v_cvt_pk_bf16_f32 v99, v102, v103
	s_nop 0
	v_permlane32_swap_b32_e32 v96, v98
	v_cvt_pk_bf16_f32 v100, v104, v105
	v_cvt_pk_bf16_f32 v101, v106, v107
	v_cvt_pk_bf16_f32 v102, v108, v109
	v_cvt_pk_bf16_f32 v103, v110, v111
	v_permlane32_swap_b32_e32 v97, v99
	v_permlane32_swap_b32_e32 v100, v102
	v_permlane32_swap_b32_e32 v101, v103
	ds_read_b64_tr_b16 v[104:105], v146 offset:0
	ds_read_b64_tr_b16 v[106:107], v146 offset:0x800
	ds_read_b64_tr_b16 v[108:109], v146 offset:0x200
	ds_read_b64_tr_b16 v[110:111], v146 offset:0xa00
	ds_read_b64_tr_b16 v[112:113], v146 offset:0x400
	ds_read_b64_tr_b16 v[114:115], v146 offset:0xc00
	ds_read_b64_tr_b16 v[116:117], v146 offset:0x600
	ds_read_b64_tr_b16 v[118:119], v146 offset:0xe00
	ds_read_b64_tr_b16 v[238:239], v146 offset:0x1000
	ds_read_b64_tr_b16 v[240:241], v146 offset:0x1800
	ds_read_b64_tr_b16 v[242:243], v146 offset:0x1200
	ds_read_b64_tr_b16 v[244:245], v146 offset:0x1a00
	ds_read_b64_tr_b16 v[246:247], v146 offset:0x1400
	ds_read_b64_tr_b16 v[248:249], v146 offset:0x1c00
	ds_read_b64_tr_b16 v[120:121], v146 offset:0x1600
	ds_read_b64_tr_b16 v[122:123], v146 offset:0x1e00
	v_fmamk_f32 v237, v236, 0x3e38aa3b, v188
	v_fmamk_f32 v236, v236, 0x3e38aa3b, v187
	v_fmamk_f32 v80, v80, 0x3e38aa3b, v237
	v_fmamk_f32 v81, v81, 0x3e38aa3b, v237
	v_fmamk_f32 v82, v82, 0x3e38aa3b, v237
	v_fmamk_f32 v83, v83, 0x3e38aa3b, v237
	v_fmamk_f32 v84, v84, 0x3e38aa3b, v237
	v_fmamk_f32 v85, v85, 0x3e38aa3b, v237
	v_fmamk_f32 v86, v86, 0x3e38aa3b, v237
	v_fmamk_f32 v87, v87, 0x3e38aa3b, v237
	s_waitcnt lgkmcnt(0)
	v_mfma_f32_32x32x16_bf16 v[0:15], v[96:99], v[104:107], v[0:15]
	v_fmamk_f32 v88, v88, 0x3e38aa3b, v237
	v_fmamk_f32 v89, v89, 0x3e38aa3b, v237
	v_fmamk_f32 v90, v90, 0x3e38aa3b, v237
	v_fmamk_f32 v91, v91, 0x3e38aa3b, v237
	v_fmamk_f32 v92, v92, 0x3e38aa3b, v237
	v_fmamk_f32 v93, v93, 0x3e38aa3b, v237
	v_fmamk_f32 v94, v94, 0x3e38aa3b, v237
	v_fmac_f32_e32 v237, 0x3e38aa3b, v95
	v_fmamk_f32 v64, v64, 0x3e38aa3b, v236
	v_fmamk_f32 v65, v65, 0x3e38aa3b, v236
	v_fmamk_f32 v66, v66, 0x3e38aa3b, v236
	v_fmamk_f32 v67, v67, 0x3e38aa3b, v236
	v_fmamk_f32 v68, v68, 0x3e38aa3b, v236
	v_fmamk_f32 v69, v69, 0x3e38aa3b, v236
	v_fmamk_f32 v70, v70, 0x3e38aa3b, v236
	v_mfma_f32_32x32x16_bf16 v[16:31], v[96:99], v[108:111], v[16:31]
	v_fmamk_f32 v71, v71, 0x3e38aa3b, v236
	v_fmamk_f32 v72, v72, 0x3e38aa3b, v236
	v_fmamk_f32 v73, v73, 0x3e38aa3b, v236
	v_fmamk_f32 v74, v74, 0x3e38aa3b, v236
	v_fmamk_f32 v75, v75, 0x3e38aa3b, v236
	v_fmamk_f32 v76, v76, 0x3e38aa3b, v236
	v_fmamk_f32 v77, v77, 0x3e38aa3b, v236
	v_fmamk_f32 v78, v78, 0x3e38aa3b, v236
	v_fmac_f32_e32 v236, 0x3e38aa3b, v79
	v_exp_f32_e32 v80, v80
	v_exp_f32_e32 v81, v81
	v_exp_f32_e32 v82, v82
	v_mfma_f32_32x32x16_bf16 v[32:47], v[96:99], v[112:115], v[32:47]
	v_exp_f32_e32 v83, v83
	v_exp_f32_e32 v84, v84
	v_exp_f32_e32 v85, v85
	v_exp_f32_e32 v86, v86
	v_exp_f32_e32 v87, v87
	v_exp_f32_e32 v88, v88
	v_exp_f32_e32 v89, v89
	v_mfma_f32_32x32x16_bf16 v[48:63], v[96:99], v[116:119], v[48:63]
	v_exp_f32_e32 v90, v90
	v_exp_f32_e32 v91, v91
	v_exp_f32_e32 v92, v92
	v_exp_f32_e32 v93, v93
	v_exp_f32_e32 v94, v94
	v_exp_f32_e32 v95, v237
	v_exp_f32_e32 v64, v64
	v_mfma_f32_32x32x16_bf16 v[0:15], v[100:103], v[238:241], v[0:15]
	v_exp_f32_e32 v65, v65
	v_exp_f32_e32 v66, v66
	v_exp_f32_e32 v67, v67
	v_exp_f32_e32 v68, v68
	v_exp_f32_e32 v69, v69
	v_exp_f32_e32 v70, v70
	v_exp_f32_e32 v71, v71
	v_mfma_f32_32x32x16_bf16 v[16:31], v[100:103], v[242:245], v[16:31]
	v_exp_f32_e32 v72, v72
	v_exp_f32_e32 v73, v73
	v_exp_f32_e32 v74, v74
	v_exp_f32_e32 v75, v75
	v_exp_f32_e32 v76, v76
	v_exp_f32_e32 v77, v77
	v_exp_f32_e32 v78, v78
	v_mfma_f32_32x32x16_bf16 v[32:47], v[100:103], v[246:249], v[32:47]
	v_exp_f32_e32 v79, v236
	v_pk_fma_f32 v[64:65], v[144:145], v[64:65], v[80:81]
	v_pk_fma_f32 v[66:67], v[144:145], v[66:67], v[82:83]
	v_pk_fma_f32 v[68:69], v[144:145], v[68:69], v[84:85]
	v_pk_fma_f32 v[70:71], v[144:145], v[70:71], v[86:87]
	v_pk_fma_f32 v[72:73], v[144:145], v[72:73], v[88:89]
	v_pk_fma_f32 v[74:75], v[144:145], v[74:75], v[90:91]
	v_mfma_f32_32x32x16_bf16 v[48:63], v[100:103], v[120:123], v[48:63]
	v_pk_fma_f32 v[76:77], v[144:145], v[76:77], v[92:93]
	v_pk_fma_f32 v[78:79], v[144:145], v[78:79], v[94:95]
	v_cvt_pk_bf16_f32 v64, v64, v65
	v_cvt_pk_bf16_f32 v65, v66, v67
	v_cvt_pk_bf16_f32 v66, v68, v69
	v_cvt_pk_bf16_f32 v67, v70, v71
	v_cvt_pk_bf16_f32 v68, v72, v73
	v_cvt_pk_bf16_f32 v69, v74, v75
	v_cvt_pk_bf16_f32 v70, v76, v77
	v_cvt_pk_bf16_f32 v71, v78, v79
	v_permlane32_swap_b32_e32 v64, v66
	v_permlane32_swap_b32_e32 v65, v67
	v_permlane32_swap_b32_e32 v68, v70
	v_permlane32_swap_b32_e32 v69, v71
	ds_read_b64_tr_b16 v[72:73], v146 offset:0x2000
	ds_read_b64_tr_b16 v[74:75], v146 offset:0x2800
	ds_read_b64_tr_b16 v[76:77], v146 offset:0x2200
	ds_read_b64_tr_b16 v[78:79], v146 offset:0x2a00
	ds_read_b64_tr_b16 v[80:81], v146 offset:0x2400
	ds_read_b64_tr_b16 v[82:83], v146 offset:0x2c00
	ds_read_b64_tr_b16 v[84:85], v146 offset:0x2600
	ds_read_b64_tr_b16 v[86:87], v146 offset:0x2e00
	s_waitcnt lgkmcnt(0)
	s_nop 0
	v_mfma_f32_32x32x16_bf16 v[0:15], v[64:67], v[72:75], v[0:15]
	ds_read_b64_tr_b16 v[72:73], v146 offset:0x3000
	ds_read_b64_tr_b16 v[74:75], v146 offset:0x3800
	v_mfma_f32_32x32x16_bf16 v[16:31], v[64:67], v[76:79], v[16:31]
	ds_read_b64_tr_b16 v[76:77], v146 offset:0x3200
	ds_read_b64_tr_b16 v[78:79], v146 offset:0x3a00
	v_mfma_f32_32x32x16_bf16 v[32:47], v[64:67], v[80:83], v[32:47]
	ds_read_b64_tr_b16 v[80:81], v146 offset:0x3400
	ds_read_b64_tr_b16 v[82:83], v146 offset:0x3c00
	ds_read_b64_tr_b16 v[88:89], v146 offset:0x3600
	ds_read_b64_tr_b16 v[90:91], v146 offset:0x3e00
	s_waitcnt lgkmcnt(0)
	v_mfma_f32_32x32x16_bf16 v[48:63], v[64:67], v[84:87], v[48:63]
	v_mfma_f32_32x32x16_bf16 v[0:15], v[68:71], v[72:75], v[0:15]
	s_add_u32 s34, s34, 0x20000
	s_addc_u32 s35, s35, 0
	v_add_u32_e32 v173, 64, v173
	s_add_i32 s93, s93, 64
	s_cmp_eq_u32 s2, s34
	v_mfma_f32_32x32x16_bf16 v[16:31], v[68:71], v[76:79], v[16:31]
	v_mfma_f32_32x32x16_bf16 v[32:47], v[68:71], v[80:83], v[32:47]
	v_mfma_f32_32x32x16_bf16 v[48:63], v[68:71], v[88:91], v[48:63]
	s_cbranch_scc1 .LBB0_326
	s_branch .LBB0_310
